# v017 plus early buffer_wbl2 by one workgroup per XCD (blockIdx<8) at each grid-barrier entry
# speedup vs baseline: 1.0036x; 1.0036x over previous
; __device__ __forceinline__ unsigned xb_ld(unsigned* p)              { return __hip_atomic_load(p, __ATOMIC_RELAXED, __HIP_MEMORY_SCOPE_AGENT); }
; __device__ __forceinline__ void xcd_barrier_complete(unsigned* bar, unsigned x, unsigned& nloc, unsigned& nx) {
;     const unsigned G = gridDim.x * gridDim.y * gridDim.z;
;     unsigned sum, cnt, mine, sp = 0u;
;     for (;;) {
;         sum = 0u; cnt = 0u; mine = 0u;
; #pragma unroll
;         for (unsigned j = 0; j < 16; ++j) { const unsigned c = xb_ld(&bar[XB_XCNT(j)]); sum += c; cnt += (c > 0u) ? 1u : 0u; mine = (j == x) ? c : mine; }
; __device__ __forceinline__ void xcd_barrier(const XcdBarrier& b) {
;     asm volatile("s_waitcnt vmcnt(0)" ::: "memory");
;     __syncthreads();
;     if (threadIdx.x == 0) {
;         unsigned* bar = b.bar;
;         __builtin_amdgcn_s_waitcnt(0);
;         unsigned nloc = b.st[0], nx = b.st[1];
;         if (nloc == 0u) { xcd_barrier_complete(bar, b.x, nloc, nx); b.st[0] = nloc; b.st[1] = nx; }
.LBB0_269:
	s_waitcnt vmcnt(0)
	s_waitcnt vmcnt(0) lgkmcnt(0)
	s_barrier
	s_and_saveexec_b64 s[4:5], s[88:89]
	s_cbranch_execz .LBB0_321
	s_cmp_gt_u32 s90, 7
	s_cbranch_scc1 .Lnowb_0
	buffer_wbl2 sc1
.Lnowb_0:
	s_add_i32 s0, 0, 0x20000
	v_mov_b32_e32 v0, s0
	s_waitcnt vmcnt(0) expcnt(0) lgkmcnt(0)
	ds_read_b32 v2, v0
	s_add_i32 s0, 0, 0x20004
	v_mov_b32_e32 v0, s0
	ds_read_b32 v0, v0
	s_waitcnt lgkmcnt(1)
	v_cmp_ne_u32_e32 vcc, 0, v2
	s_cbranch_vccnz .LBB0_285
	s_add_u32 s6, s86, 0x20c28200
	s_addc_u32 s7, s87, 0
	s_add_u32 s8, s86, 0x20c28400
	s_addc_u32 s9, s87, 0
	s_add_u32 s10, s86, 0x20c28500
	s_addc_u32 s11, s87, 0
	s_add_u32 s12, s86, 0x20c28600
	s_addc_u32 s13, s87, 0
	s_add_u32 s14, s86, 0x20c28700
	s_addc_u32 s15, s87, 0
	s_add_u32 s16, s86, 0x20c28800
	s_addc_u32 s17, s87, 0
	s_add_u32 s18, s86, 0x20c28900
	s_addc_u32 s19, s87, 0
	s_add_u32 s20, s86, 0x20c28a00
	s_addc_u32 s21, s87, 0
	s_add_u32 s22, s86, 0x20c28b00
	s_addc_u32 s23, s87, 0
	s_add_u32 s24, s86, 0x20c28c00
	s_addc_u32 s25, s87, 0
	s_add_u32 s26, s86, 0x20c28d00
	s_addc_u32 s27, s87, 0
	s_add_u32 s28, s86, 0x20c28e00
	s_addc_u32 s29, s87, 0
	s_add_u32 s30, s86, 0x20c28f00
	s_addc_u32 s31, s87, 0
	s_add_u32 s34, s86, 0x20c29000
	s_addc_u32 s35, s87, 0
	s_add_u32 s36, s86, 0x20c29100
	s_addc_u32 s37, s87, 0
	s_add_u32 s38, s86, 0x20c29200
	s_addc_u32 s39, s87, 0
	s_mul_i32 s0, s73, s85
	s_add_u32 s40, s86, 0x20c29300
	s_mul_i32 s0, s0, s72
	s_addc_u32 s41, s87, 0
	s_mov_b32 s1, 1
	v_mov_b32_e32 v16, 0
	s_branch .LBB0_273

; __device__ __forceinline__ unsigned xb_ld(unsigned* p)              { return __hip_atomic_load(p, __ATOMIC_RELAXED, __HIP_MEMORY_SCOPE_AGENT); }
; __device__ __forceinline__ void xcd_barrier_complete(unsigned* bar, unsigned x, unsigned& nloc, unsigned& nx) {
;     const unsigned G = gridDim.x * gridDim.y * gridDim.z;
;     unsigned sum, cnt, mine, sp = 0u;
;     for (;;) {
;         sum = 0u; cnt = 0u; mine = 0u;
; #pragma unroll
;         for (unsigned j = 0; j < 16; ++j) { const unsigned c = xb_ld(&bar[XB_XCNT(j)]); sum += c; cnt += (c > 0u) ? 1u : 0u; mine = (j == x) ? c : mine; }
; __device__ __forceinline__ void xcd_barrier(const XcdBarrier& b) {
;     asm volatile("s_waitcnt vmcnt(0)" ::: "memory");
;     __syncthreads();
;     if (threadIdx.x == 0) {
;         unsigned* bar = b.bar;
;         __builtin_amdgcn_s_waitcnt(0);
;         unsigned nloc = b.st[0], nx = b.st[1];
;         if (nloc == 0u) { xcd_barrier_complete(bar, b.x, nloc, nx); b.st[0] = nloc; b.st[1] = nx; }
.LBB0_363:
	s_waitcnt vmcnt(0)
	s_waitcnt lgkmcnt(0)
	s_barrier
	s_and_saveexec_b64 s[6:7], s[88:89]
	s_cbranch_execz .LBB0_415
	s_cmp_gt_u32 s90, 7
	s_cbranch_scc1 .Lnowb_1
	buffer_wbl2 sc1
.Lnowb_1:
	s_add_i32 s0, 0, 0x20000
	v_mov_b32_e32 v0, s0
	s_waitcnt vmcnt(0) expcnt(0) lgkmcnt(0)
	ds_read_b32 v2, v0
	s_add_i32 s0, 0, 0x20004
	v_mov_b32_e32 v0, s0
	ds_read_b32 v0, v0
	s_waitcnt lgkmcnt(1)
	v_cmp_ne_u32_e32 vcc, 0, v2
	s_cbranch_vccnz .LBB0_379
	s_add_u32 s8, s86, 0x20c28200
	s_addc_u32 s9, s87, 0
	s_add_u32 s10, s86, 0x20c28400
	s_addc_u32 s11, s87, 0
	s_add_u32 s12, s86, 0x20c28500
	s_addc_u32 s13, s87, 0
	s_add_u32 s14, s86, 0x20c28600
	s_addc_u32 s15, s87, 0
	s_add_u32 s16, s86, 0x20c28700
	s_addc_u32 s17, s87, 0
	s_add_u32 s18, s86, 0x20c28800
	s_addc_u32 s19, s87, 0
	s_add_u32 s20, s86, 0x20c28900
	s_addc_u32 s21, s87, 0
	s_add_u32 s22, s86, 0x20c28a00
	s_addc_u32 s23, s87, 0
	s_add_u32 s24, s86, 0x20c28b00
	s_addc_u32 s25, s87, 0
	s_add_u32 s26, s86, 0x20c28c00
	s_addc_u32 s27, s87, 0
	s_add_u32 s28, s86, 0x20c28d00
	s_addc_u32 s29, s87, 0
	s_add_u32 s30, s86, 0x20c28e00
	s_addc_u32 s31, s87, 0
	s_add_u32 s34, s86, 0x20c28f00
	s_addc_u32 s35, s87, 0
	s_add_u32 s36, s86, 0x20c29000
	s_addc_u32 s37, s87, 0
	s_add_u32 s38, s86, 0x20c29100
	s_addc_u32 s39, s87, 0
	s_add_u32 s40, s86, 0x20c29200
	s_addc_u32 s41, s87, 0
	s_mul_i32 s0, s73, s85
	s_add_u32 s42, s86, 0x20c29300
	s_mul_i32 s0, s0, s72
	s_addc_u32 s43, s87, 0
	s_mov_b32 s1, 1
	v_mov_b32_e32 v16, 0
	s_branch .LBB0_367

; __device__ __forceinline__ void xcd_barrier(const XcdBarrier& b) {
;     asm volatile("s_waitcnt vmcnt(0)" ::: "memory");
;     __syncthreads();
;     if (threadIdx.x == 0) {
;         unsigned* bar = b.bar;
;         __builtin_amdgcn_s_waitcnt(0);
;         unsigned nloc = b.st[0], nx = b.st[1];
;         if (nloc == 0u) { xcd_barrier_complete(bar, b.x, nloc, nx); b.st[0] = nloc; b.st[1] = nx; }
.LBB0_477:
	s_waitcnt vmcnt(0)
	s_waitcnt vmcnt(0) lgkmcnt(0)
	s_barrier
	s_and_saveexec_b64 s[6:7], s[88:89]
	s_cbranch_execz .LBB0_529
	s_cmp_gt_u32 s90, 7
	s_cbranch_scc1 .Lnowb_2
	buffer_wbl2 sc1

; __device__ __forceinline__ unsigned xb_ld(unsigned* p)              { return __hip_atomic_load(p, __ATOMIC_RELAXED, __HIP_MEMORY_SCOPE_AGENT); }
; __device__ __forceinline__ void xcd_barrier_complete(unsigned* bar, unsigned x, unsigned& nloc, unsigned& nx) {
;     const unsigned G = gridDim.x * gridDim.y * gridDim.z;
;     unsigned sum, cnt, mine, sp = 0u;
;     for (;;) {
;         sum = 0u; cnt = 0u; mine = 0u;
; #pragma unroll
;         for (unsigned j = 0; j < 16; ++j) { const unsigned c = xb_ld(&bar[XB_XCNT(j)]); sum += c; cnt += (c > 0u) ? 1u : 0u; mine = (j == x) ? c : mine; }
; __device__ __forceinline__ void xcd_barrier(const XcdBarrier& b) {
;     asm volatile("s_waitcnt vmcnt(0)" ::: "memory");
;     __syncthreads();
;     if (threadIdx.x == 0) {
;         unsigned* bar = b.bar;
;         __builtin_amdgcn_s_waitcnt(0);
;         unsigned nloc = b.st[0], nx = b.st[1];
;         if (nloc == 0u) { xcd_barrier_complete(bar, b.x, nloc, nx); b.st[0] = nloc; b.st[1] = nx; }
.LBB0_1228:
	s_waitcnt vmcnt(0)
	s_waitcnt lgkmcnt(0)
	s_barrier
	s_and_saveexec_b64 s[2:3], s[88:89]
	s_cbranch_execz .LBB0_1280
	s_cmp_gt_u32 s90, 7
	s_cbranch_scc1 .Lnowb_9
	buffer_wbl2 sc1
.Lnowb_9:
	s_add_i32 s0, 0, 0x20000
	v_mov_b32_e32 v0, s0
	s_waitcnt vmcnt(0) expcnt(0) lgkmcnt(0)
	ds_read_b32 v2, v0
	s_add_i32 s0, 0, 0x20004
	v_mov_b32_e32 v0, s0
	ds_read_b32 v0, v0
	s_waitcnt lgkmcnt(1)
	v_cmp_ne_u32_e32 vcc, 0, v2
	s_cbranch_vccnz .LBB0_1244
	s_add_u32 s4, s86, 0x20c28200
	s_addc_u32 s5, s87, 0
	s_add_u32 s6, s86, 0x20c28400
	s_addc_u32 s7, s87, 0
	s_add_u32 s8, s86, 0x20c28500
	s_addc_u32 s9, s87, 0
	s_add_u32 s10, s86, 0x20c28600
	s_addc_u32 s11, s87, 0
	s_add_u32 s12, s86, 0x20c28700
	s_addc_u32 s13, s87, 0
	s_add_u32 s14, s86, 0x20c28800
	s_addc_u32 s15, s87, 0
	s_add_u32 s16, s86, 0x20c28900
	s_addc_u32 s17, s87, 0
	s_add_u32 s18, s86, 0x20c28a00
	s_addc_u32 s19, s87, 0
	s_add_u32 s20, s86, 0x20c28b00
	s_addc_u32 s21, s87, 0
	s_add_u32 s22, s86, 0x20c28c00
	s_addc_u32 s23, s87, 0
	s_add_u32 s24, s86, 0x20c28d00
	s_addc_u32 s25, s87, 0
	s_add_u32 s26, s86, 0x20c28e00
	s_addc_u32 s27, s87, 0
	s_add_u32 s28, s86, 0x20c28f00
	s_addc_u32 s29, s87, 0
	s_add_u32 s30, s86, 0x20c29000
	s_addc_u32 s31, s87, 0
	s_add_u32 s34, s86, 0x20c29100
	s_addc_u32 s35, s87, 0
	s_add_u32 s36, s86, 0x20c29200
	s_addc_u32 s37, s87, 0
	s_mul_i32 s0, s73, s85
	s_add_u32 s38, s86, 0x20c29300
	s_mul_i32 s0, s0, s72
	s_addc_u32 s39, s87, 0
	s_mov_b32 s1, 1
	v_mov_b32_e32 v16, 0
	s_branch .LBB0_1232
